# key-norm bound load of the terminating heads issued before the q-fragment wait; memory-attention unit prologue drains only before its loop
# speedup vs baseline: 1.0017x; 1.0017x over previous
.Lsp_par_done:
	v_readfirstlane_b32 s21, v5
	s_ashr_i32 s20, s21, 6
	s_add_i32 s80, s25, -1
	v_bfe_u32 v0, v5, 4, 2
	s_and_b32 s22, s20, 3
	s_lshl_b32 s26, s20, 3
	s_ashr_i32 s81, s80, 31
	v_or_b32_e32 v4, s26, v0
	v_lshlrev_b32_e32 v6, 5, v0
	v_bitop3_b32 v0, s26, v5, v0 bitop3:0x36
	s_lshl_b32 s30, s22, 5
	s_max_i32 s31, s25, 2
	s_lshl_b64 s[26:27], s[80:81], 16
	v_and_b32_e32 v3, 15, v5
	v_lshlrev_b32_e32 v8, 9, v4
	v_lshlrev_b32_e32 v0, 3, v0
	s_add_u32 s28, s48, s26
	v_lshlrev_b32_e32 v7, 3, v3
	v_and_or_b32 v0, v0, s11, v8
	s_addc_u32 s29, s49, s27
	v_lshlrev_b32_e32 v188, 1, v0
	v_bitop3_b32 v0, v8, v6, v7 bitop3:0xf6
	s_add_u32 s34, s60, s26
	v_lshlrev_b32_e32 v190, 1, v0
	v_or_b32_e32 v0, 4, v4
	v_bitop3_b32 v4, v4, v5, 4 bitop3:0x36
	s_addc_u32 s35, s61, s27
	s_lshl_b32 s26, s20, 11
	v_lshlrev_b32_e32 v0, 9, v0
	v_lshlrev_b32_e32 v4, 3, v4
	s_add_i32 s26, s26, 0
	v_mov_b32_e32 v189, v1
	v_and_or_b32 v4, v4, s11, v0
	s_add_i32 s27, s26, 0x4000
	v_lshl_add_u64 v[8:9], s[28:29], 0, v[188:189]
	s_mov_b32 m0, s26
	s_nop 0
	global_load_lds_dwordx4 v[8:9], off
	v_mov_b32_e32 v191, v1
	v_lshlrev_b32_e32 v192, 1, v4
	v_bitop3_b32 v0, v0, v6, v7 bitop3:0xf6
	v_lshl_add_u64 v[8:9], s[34:35], 0, v[190:191]
	s_mov_b32 m0, s27
	s_nop 0
	global_load_lds_dwordx4 v[8:9], off
	v_mov_b32_e32 v193, v1
	s_add_i32 s27, s26, 0x400
	s_add_i32 s72, s31, -2
	v_lshlrev_b32_e32 v194, 1, v0
	v_lshl_add_u64 v[8:9], s[28:29], 0, v[192:193]
	s_mov_b32 m0, s27
	s_nop 0
	global_load_lds_dwordx4 v[8:9], off
	v_mov_b32_e32 v195, v1
	s_add_i32 s27, s26, 0x4400
	s_ashr_i32 s46, s21, 8
	s_lshl_b64 s[28:29], s[72:73], 16
	v_lshl_add_u64 v[8:9], s[34:35], 0, v[194:195]
	s_add_u32 s34, s48, s28
	s_addc_u32 s35, s49, s29
	s_add_u32 s28, s60, s28
	s_mov_b32 m0, s27
	s_nop 0
	global_load_lds_dwordx4 v[8:9], off
	s_addc_u32 s29, s61, s29
	v_lshl_add_u64 v[8:9], s[34:35], 0, v[188:189]
	v_and_b32_e32 v2, 31, v5
	s_add_i32 s27, s26, 0x8000
	s_mov_b32 m0, s27
	s_nop 0
	global_load_lds_dwordx4 v[8:9], off
	v_lshl_add_u64 v[8:9], s[28:29], 0, v[190:191]
	s_add_i32 s31, s26, 0xc000
	s_mov_b32 m0, s31
	s_nop 0
	global_load_lds_dwordx4 v[8:9], off
	v_lshl_add_u64 v[8:9], s[34:35], 0, v[192:193]
	v_or_b32_e32 v226, s30, v2
	s_add_i32 s27, s26, 0x8400
	s_mov_b32 m0, s27
	s_nop 0
	global_load_lds_dwordx4 v[8:9], off
	v_lshl_add_u64 v[8:9], s[28:29], 0, v[194:195]
	v_lshlrev_b32_e32 v0, 11, v226
	s_lshl_b32 s28, s46, 6
	v_bfe_u32 v4, v5, 5, 1
	s_add_i32 s27, s26, 0xc400
	s_mov_b32 m0, s27
	s_nop 0
	global_load_lds_dwordx4 v[8:9], off
	v_lshl_add_u64 v[8:9], s[38:39], 0, v[0:1]
	s_ashr_i32 s29, s28, 31
	v_lshl_add_u64 v[8:9], s[28:29], 1, v[8:9]
	v_lshlrev_b32_e32 v0, 4, v4
	v_lshl_add_u64 v[8:9], v[8:9], 0, v[0:1]
	global_load_dwordx4 v[144:147], v[8:9], off
	global_load_dwordx4 v[148:151], v[8:9], off offset:32
	global_load_dwordx4 v[152:155], v[8:9], off offset:64
	global_load_dwordx4 v[156:159], v[8:9], off offset:96
	v_readlane_b32 s12, v253, 34
	v_readlane_b32 s13, v253, 35
	v_and_b32_e32 v203, 63, v5
	s_or_b64 s[82:83], s[0:1], s[12:13]
	v_mov_b32_e32 v231, 0x7f61b1e6
	s_and_b64 vcc, exec, s[82:83]
	v_cmp_eq_u32_e64 s[0:1], 0, v203
	s_cbranch_vccnz .LBB0_455
	s_lshl_b32 s72, s36, 1
	s_lshl_b64 s[28:29], s[72:73], 2
	v_readlane_b32 s12, v253, 25
	v_readlane_b32 s13, v253, 26
	s_add_u32 s27, s12, s28
	s_addc_u32 s31, s13, s29
	s_ashr_i32 s47, s46, 31
	s_lshl_b64 s[28:29], s[46:47], 2
	s_add_u32 s28, s27, s28
	s_addc_u32 s29, s31, s29
	s_nop 0
	global_load_dword v223, v1, s[28:29]
	s_waitcnt vmcnt(1)
	v_and_b32_e32 v7, 0xffff0000, v144
	v_lshlrev_b32_e32 v0, 16, v144
	v_mul_f32_e32 v7, v7, v7
	v_fmac_f32_e32 v7, v0, v0
	v_lshlrev_b32_e32 v0, 16, v145
	v_fmac_f32_e32 v7, v0, v0
	v_and_b32_e32 v0, 0xffff0000, v145
	v_fmac_f32_e32 v7, v0, v0
	v_lshlrev_b32_e32 v8, 16, v146
	v_fmac_f32_e32 v7, v8, v8
	v_and_b32_e32 v8, 0xffff0000, v146
	v_fmac_f32_e32 v7, v8, v8
	v_lshlrev_b32_e32 v8, 16, v147
	v_fmac_f32_e32 v7, v8, v8
	v_and_b32_e32 v8, 0xffff0000, v147
	v_fmac_f32_e32 v7, v8, v8
	v_lshlrev_b32_e32 v8, 16, v148
	v_fmac_f32_e32 v7, v8, v8
	v_and_b32_e32 v8, 0xffff0000, v148
	v_fmac_f32_e32 v7, v8, v8
	v_lshlrev_b32_e32 v8, 16, v149
	v_fmac_f32_e32 v7, v8, v8
	v_and_b32_e32 v8, 0xffff0000, v149
	v_fmac_f32_e32 v7, v8, v8
	v_lshlrev_b32_e32 v8, 16, v150
	v_fmac_f32_e32 v7, v8, v8
	v_and_b32_e32 v8, 0xffff0000, v150
	v_fmac_f32_e32 v7, v8, v8
	v_lshlrev_b32_e32 v8, 16, v151
	v_fmac_f32_e32 v7, v8, v8
	v_and_b32_e32 v8, 0xffff0000, v151
	v_fmac_f32_e32 v7, v8, v8
	v_lshlrev_b32_e32 v8, 16, v152
	v_fmac_f32_e32 v7, v8, v8
	v_and_b32_e32 v8, 0xffff0000, v152
	v_fmac_f32_e32 v7, v8, v8
	v_lshlrev_b32_e32 v8, 16, v153
	v_fmac_f32_e32 v7, v8, v8
	v_and_b32_e32 v8, 0xffff0000, v153
	v_fmac_f32_e32 v7, v8, v8
	v_lshlrev_b32_e32 v8, 16, v154
	v_fmac_f32_e32 v7, v8, v8
	v_and_b32_e32 v8, 0xffff0000, v154
	v_fmac_f32_e32 v7, v8, v8
	v_lshlrev_b32_e32 v8, 16, v155
	v_fmac_f32_e32 v7, v8, v8
	v_and_b32_e32 v8, 0xffff0000, v155
	v_fmac_f32_e32 v7, v8, v8
	v_and_b32_e32 v9, 0xffff0000, v156
	v_lshlrev_b32_e32 v8, 16, v156
	v_pk_mul_f32 v[8:9], v[8:9], v[8:9]
	s_mov_b32 s12, 0xf800000
	v_add_f32_e32 v7, v8, v7
	v_add_f32_e32 v7, v9, v7
	v_and_b32_e32 v9, 0xffff0000, v157
	v_lshlrev_b32_e32 v8, 16, v157
	v_pk_mul_f32 v[8:9], v[8:9], v[8:9]
	s_nop 0
	v_add_f32_e32 v7, v8, v7
	v_add_f32_e32 v7, v9, v7
	v_and_b32_e32 v9, 0xffff0000, v158
	v_lshlrev_b32_e32 v8, 16, v158
	v_pk_mul_f32 v[8:9], v[8:9], v[8:9]
	s_nop 0
	v_add_f32_e32 v7, v8, v7
	v_add_f32_e32 v7, v9, v7
	v_and_b32_e32 v9, 0xffff0000, v159
	v_lshlrev_b32_e32 v8, 16, v159
	v_pk_mul_f32 v[8:9], v[8:9], v[8:9]
	s_nop 0
	v_add_f32_e32 v7, v8, v7
	v_add_f32_e32 v7, v9, v7
	ds_bpermute_b32 v8, v225, v7
	s_waitcnt lgkmcnt(0)
	v_add_f32_e32 v7, v7, v8
	v_mul_f32_e32 v8, 0x4f800000, v7
	v_cmp_gt_f32_e32 vcc, s12, v7
	s_nop 1
	v_cndmask_b32_e32 v7, v7, v8, vcc
	v_sqrt_f32_e32 v8, v7
	s_nop 0
	v_add_u32_e32 v9, -1, v8
	v_fma_f32 v10, -v9, v8, v7
	v_cmp_ge_f32_e64 s[38:39], 0, v10
	v_add_u32_e32 v10, 1, v8
	v_fma_f32 v11, -v10, v8, v7
	v_cmp_lt_f32_e64 s[42:43], 0, v11
	s_and_saveexec_b64 s[84:85], s[0:1]
	s_cbranch_execz .LBB0_454
	s_lshl_b32 s0, s20, 2
	s_add_i32 s0, s0, 0
	s_add_i32 s0, s0, 0x20040
	v_mov_b32_e32 v11, s0
	ds_write_b32 v11, v1
	ds_write_b32 v11, v1 offset:32
.LBB0_454:
	s_or_b64 exec, exec, s[84:85]
	v_cndmask_b32_e64 v8, v8, v9, s[38:39]
	v_cndmask_b32_e64 v8, v8, v10, s[42:43]
	v_mul_f32_e32 v9, 0x37800000, v8
	v_cndmask_b32_e32 v8, v8, v9, vcc
	v_cmp_class_f32_e32 vcc, v7, v208
	s_mov_b32 s0, 0x3f8147ae
	s_nop 0
	v_cndmask_b32_e32 v7, v8, v7, vcc
	s_waitcnt vmcnt(0)
	v_mul_f32_e32 v0, v223, v7
	v_fma_f32 v231, v0, s0, 0.5

.LBB0_525:
	v_lshlrev_b32_e32 v0, 8, v5
	v_xor_b32_e32 v5, v156, v3
	v_lshl_or_b32 v158, v5, 4, v0
	v_bitop3_b32 v5, v156, v3, 2 bitop3:0x36
	v_lshl_or_b32 v159, v5, 4, v0
	v_bitop3_b32 v5, v156, v3, 4 bitop3:0x36
	v_lshl_or_b32 v160, v5, 4, v0
	v_bitop3_b32 v5, v156, v3, 6 bitop3:0x36
	v_lshl_or_b32 v161, v5, 4, v0
	v_bitop3_b32 v5, v156, v3, 8 bitop3:0x36
	v_lshl_or_b32 v162, v5, 4, v0
	v_bitop3_b32 v5, v156, v3, 10 bitop3:0x36
	v_lshl_or_b32 v163, v5, 4, v0
	v_bitop3_b32 v5, v156, v3, 12 bitop3:0x36
	v_lshl_or_b32 v164, v5, 4, v0
	v_bitop3_b32 v5, v156, v3, 14 bitop3:0x36
	v_lshl_or_b32 v165, v5, 4, v0
	v_lshrrev_b32_e32 v0, 2, v3
	v_lshlrev_b32_e32 v3, 10, v156
	v_lshlrev_b32_e32 v5, 8, v0
	v_and_b32_e32 v4, 32, v4
	v_lshlrev_b32_e32 v2, 3, v2
	v_or3_b32 v3, v3, v5, v4
	v_and_b32_e32 v2, 24, v2
	v_lshlrev_b32_e32 v0, 6, v0
	v_or3_b32 v0, v3, v2, v0
	s_movk_i32 s12, 0x80
	s_ashr_i32 s25, s25, 7
	v_bitop3_b32 v168, v0, s12, v217 bitop3:0x36
	s_movk_i32 s12, 0xc0
	v_mov_b32_e32 v14, v1
	v_mov_b32_e32 v15, v1
	s_add_i32 s25, s25, 0x100000
	v_or_b32_e32 v166, 0x4000, v0
	v_bitop3_b32 v167, v0, 64, v217 bitop3:0x36
	v_bitop3_b32 v169, v0, s12, v217 bitop3:0x36
	v_mov_b32_e32 v0, v1
	v_mov_b32_e32 v2, v1
	v_mov_b32_e32 v3, v1
	v_mov_b32_e32 v4, v1
	v_mov_b32_e32 v5, v1
	v_mov_b32_e32 v6, v1
	v_mov_b32_e32 v7, v1
	v_mov_b32_e32 v8, v1
	v_mov_b32_e32 v9, v1
	v_mov_b32_e32 v10, v1
	v_mov_b32_e32 v11, v1
	v_mov_b32_e32 v12, v1
	v_mov_b32_e32 v13, v1
	v_mov_b64_e32 v[64:65], v[14:15]
	v_mov_b64_e32 v[48:49], v[14:15]
	v_mov_b64_e32 v[32:33], v[14:15]
	s_cmp_gt_i32 s19, 3
	v_mov_b64_e32 v[62:63], v[12:13]
	v_mov_b64_e32 v[60:61], v[10:11]
	v_mov_b64_e32 v[58:59], v[8:9]
	v_mov_b64_e32 v[56:57], v[6:7]
	v_mov_b64_e32 v[54:55], v[4:5]
	v_mov_b64_e32 v[52:53], v[2:3]
	v_mov_b64_e32 v[50:51], v[0:1]
	v_mov_b64_e32 v[46:47], v[12:13]
	v_mov_b64_e32 v[44:45], v[10:11]
	v_mov_b64_e32 v[42:43], v[8:9]
	v_mov_b64_e32 v[40:41], v[6:7]
	v_mov_b64_e32 v[38:39], v[4:5]
	v_mov_b64_e32 v[36:37], v[2:3]
	v_mov_b64_e32 v[34:35], v[0:1]
	v_mov_b64_e32 v[30:31], v[12:13]
	v_mov_b64_e32 v[28:29], v[10:11]
	v_mov_b64_e32 v[26:27], v[8:9]
	v_mov_b64_e32 v[24:25], v[6:7]
	v_mov_b64_e32 v[22:23], v[4:5]
	v_mov_b64_e32 v[20:21], v[2:3]
	v_mov_b64_e32 v[18:19], v[0:1]
	v_mov_b64_e32 v[16:17], v[14:15]
	s_mov_b32 s26, 3
	s_cselect_b64 s[48:49], -1, 0
	s_mov_b32 s27, 0
	s_mov_b64 s[60:61], 0
	v_mov_b32_e32 v170, 0xf149f2ca
	v_mov_b32_e32 v157, 0
	v_mov_b32_e32 v130, 0
	v_mov_b32_e32 v131, 0
	v_mov_b32_e32 v132, 0
	v_mov_b32_e32 v133, 0
	v_mov_b32_e32 v134, 0
	v_mov_b32_e32 v135, 0
	v_mov_b32_e32 v136, 0
	v_mov_b32_e32 v137, 0
	v_mov_b32_e32 v138, 0
	v_mov_b32_e32 v139, 0
	v_mov_b32_e32 v140, 0
	v_mov_b32_e32 v141, 0
	v_mov_b32_e32 v142, 0
	v_mov_b32_e32 v143, 0
	v_mov_b32_e32 v144, 0
	v_mov_b32_e32 v145, 0
	v_mov_b64_e32 v[14:15], v[12:13]
	v_mov_b64_e32 v[12:13], v[10:11]
	v_mov_b64_e32 v[10:11], v[8:9]
	v_mov_b64_e32 v[8:9], v[6:7]
	v_mov_b64_e32 v[6:7], v[4:5]
	v_mov_b64_e32 v[4:5], v[2:3]
	v_mov_b64_e32 v[2:3], v[0:1]
	s_mov_b32 s28, 0
	s_waitcnt vmcnt(7)
	s_waitcnt vmcnt(6)
	s_waitcnt vmcnt(5)
	s_waitcnt vmcnt(4)
	s_waitcnt vmcnt(3)
	s_waitcnt vmcnt(2)
	s_waitcnt vmcnt(1)
	s_waitcnt vmcnt(0)
